# out-proj L0 epilogue (f32 residual input): 14 of 16 serialized read-modify-write iterations served from two register prefetch batches
# baseline (speedup 1.0000x reference)
;     __device__ __forceinline__ void operator()(f32x4 (&acc)[2][2][4][2], const Unit& u, int wr, int wc, int fr, int fq) const {
;         const int row0 = u.pm * BM + wr * 64 + fr, col0 = u.pn * BM + wc * 32 + 8 * fq;
;         const int r = u.pm < 32 ? (u.pm >> 3) : 4;
;         const float* gt = mod + (size_t)r * MODW + gate_off + col0;
;         f32x4 gv[2][2];
; #pragma unroll
;         for (int bj = 0; bj < 2; ++bj)
; #pragma unroll
;             for (int n = 0; n < 2; ++n) gv[bj][n] = *(const f32x4*)(gt + bj * HALF + 4 * n);
;         if (u.ks >= 0) {
;             float* pb = PART + ((size_t)u.ks * TC + (size_t)(row0 - TL)) * DM + col0;
; #pragma unroll
;             for (int ai = 0; ai < 2; ++ai)
; #pragma unroll
;                 for (int m = 0; m < 4; ++m)
; #pragma unroll
;                     for (int bj = 0; bj < 2; ++bj) { float* q = pb + (size_t)(ai * HALF + m * 16) * DM + bj * HALF;
;                         *(f32x4*)q = gv[bj][0] * acc[ai][bj][m][0]; *(f32x4*)(q + 4) = gv[bj][1] * acc[ai][bj][m][1]; }
;             return;
;         }
; #pragma unroll
;         for (int ai = 0; ai < 2; ++ai)
; #pragma unroll
;             for (int m = 0; m < 4; ++m) { const size_t ro = (size_t)(row0 + ai * HALF + m * 16) * DM + col0;
; #pragma unroll
;                 for (int bj = 0; bj < 2; ++bj) { f32x4 x0, x1;
;                     if (Xf32 != nullptr) { x0 = *(const f32x4*)(Xf32 + ro + bj * HALF); x1 = *(const f32x4*)(Xf32 + ro + bj * HALF + 4); }
.LBB0_671:
	v_lshl_or_b32 v162, s50, 8, v172
	s_lshl_b64 s[50:51], s[52:53], 2
	s_add_u32 s50, s2, s50
	s_addc_u32 s51, s3, s51
	v_ashrrev_i32_e32 v163, 31, v162
	v_lshl_add_u64 v[128:129], v[162:163], 2, s[50:51]
	s_mov_b64 s[50:51], 0x12104000
	s_mov_b32 s9, 0x12104000
	v_lshl_add_u64 v[132:133], v[128:129], 0, s[50:51]
	v_add_co_u32_e32 v128, vcc, s9, v128
	v_lshl_add_u32 v164, s8, 8, v170
	s_nop 0
	v_addc_co_u32_e32 v129, vcc, 0, v129, vcc
	global_load_dwordx4 v[140:143], v[128:129], off
	s_nop 0
	global_load_dwordx4 v[128:131], v[132:133], off offset:528
	global_load_dwordx4 v[136:139], v[132:133], off offset:16
	s_nop 0
	global_load_dwordx4 v[132:135], v[132:133], off offset:512
	s_mov_b64 s[8:9], -1
	s_cmp_gt_i32 s28, -1
	v_ashrrev_i32_e32 v165, 31, v164
	s_cbranch_scc1 .LBB0_722
	v_lshlrev_b64 v[144:145], 11, v[164:165]
	v_lshl_add_u64 v[166:167], v[144:145], 0, v[162:163]
	s_and_b64 vcc, exec, s[26:27]
	v_lshl_add_u64 v[168:169], v[166:167], 2, s[14:15]
	s_cbranch_vccz .LBB0_726
	v_mov_b64_e32 v[244:245], v[168:169]
	v_mov_b32_e32 v243, 0
	v_mov_b32_e32 v242, 0x0
	v_lshl_add_u64 v[180:181], v[244:245], 0, v[242:243]
	global_load_dwordx4 v[176:179], v[180:181], off offset:16
	global_load_dwordx4 v[180:183], v[180:181], off
	v_mov_b32_e32 v242, 0x0
	v_lshl_add_u64 v[188:189], v[244:245], 0, v[242:243]
	global_load_dwordx4 v[184:187], v[188:189], off offset:528
	global_load_dwordx4 v[188:191], v[188:189], off offset:512
	v_mov_b32_e32 v242, 0x20000
	v_lshl_add_u64 v[196:197], v[244:245], 0, v[242:243]
	global_load_dwordx4 v[192:195], v[196:197], off offset:16
	global_load_dwordx4 v[196:199], v[196:197], off
	v_mov_b32_e32 v242, 0x20000
	v_lshl_add_u64 v[204:205], v[244:245], 0, v[242:243]
	global_load_dwordx4 v[200:203], v[204:205], off offset:528
	global_load_dwordx4 v[204:207], v[204:205], off offset:512
	v_mov_b32_e32 v242, 0x40000
	v_lshl_add_u64 v[212:213], v[244:245], 0, v[242:243]
	global_load_dwordx4 v[208:211], v[212:213], off offset:16
	global_load_dwordx4 v[212:215], v[212:213], off
	v_mov_b32_e32 v242, 0x40000
	v_lshl_add_u64 v[230:231], v[244:245], 0, v[242:243]
	global_load_dwordx4 v[226:229], v[230:231], off offset:528
	global_load_dwordx4 v[230:233], v[230:231], off offset:512
	v_mov_b32_e32 v242, 0x60000
	v_lshl_add_u64 v[238:239], v[244:245], 0, v[242:243]
	global_load_dwordx4 v[234:237], v[238:239], off offset:16
	global_load_dwordx4 v[238:241], v[238:239], off
	v_lshl_add_u64 v[166:167], v[166:167], 1, s[20:21]
	s_cbranch_execnz .LBB0_675

; __device__ __forceinline__ unsigned cvt_pk_bf16(float lo, float hi) { unsigned r; asm volatile("v_cvt_pk_bf16_f32 %0, %1, %2" : "=v"(r) : "v"(lo), "v"(hi)); return r; }
; __device__ __forceinline__ float lo_f(unsigned w) { return __uint_as_float(w << 16); }
; __device__ __forceinline__ float hi_f(unsigned w) { return __uint_as_float(w & 0xffff0000u); }
;     __device__ __forceinline__ void operator()(f32x4 (&acc)[2][2][4][2], const Unit& u, int wr, int wc, int fr, int fq) const {
;     ...
; #pragma unroll
;         for (int ai = 0; ai < 2; ++ai)
; #pragma unroll
;             for (int m = 0; m < 4; ++m) { const size_t ro = (size_t)(row0 + ai * HALF + m * 16) * DM + col0;
; #pragma unroll
;                 for (int bj = 0; bj < 2; ++bj) { f32x4 x0, x1;
;                     if (Xf32 != nullptr) { x0 = *(const f32x4*)(Xf32 + ro + bj * HALF); x1 = *(const f32x4*)(Xf32 + ro + bj * HALF + 4); }
;                     else { const u32x4 xb = *(const u32x4*)(X + ro + bj * HALF);
;                         x0 = (f32x4){lo_f(xb.x), hi_f(xb.x), lo_f(xb.y), hi_f(xb.y)}; x1 = (f32x4){lo_f(xb.z), hi_f(xb.z), lo_f(xb.w), hi_f(xb.w)}; }
;                     x0 += gv[bj][0] * acc[ai][bj][m][0]; x1 += gv[bj][1] * acc[ai][bj][m][1];
;                     u32x4 w; w.x = cvt_pk_bf16(x0[0], x0[1]); w.y = cvt_pk_bf16(x0[2], x0[3]); w.z = cvt_pk_bf16(x1[0], x1[1]); w.w = cvt_pk_bf16(x1[2], x1[3]);
;                     *(u32x4*)(X + ro + bj * HALF) = w; } }
.LBB0_675:
	s_waitcnt vmcnt(0)
	v_mov_b64_e32 v[148:149], v[180:181]
	v_mov_b64_e32 v[150:151], v[182:183]
	v_mov_b64_e32 v[144:145], v[176:177]
	v_mov_b64_e32 v[146:147], v[178:179]
	v_pk_fma_f32 v[148:149], v[124:125], v[140:141], v[148:149]
	v_pk_fma_f32 v[174:175], v[122:123], v[138:139], v[146:147]
	v_pk_fma_f32 v[146:147], v[120:121], v[136:137], v[144:145]
	v_cvt_pk_bf16_f32 v144, v148, v149
	v_cndmask_b32_e64 v148, 0, 1, s[26:27]
	v_cmp_ne_u32_e64 s[8:9], 1, v148
	s_andn2_b64 vcc, exec, s[26:27]
	v_pk_fma_f32 v[150:151], v[126:127], v[142:143], v[150:151]
	s_nop 0
	v_cvt_pk_bf16_f32 v145, v150, v151
	v_cvt_pk_bf16_f32 v146, v146, v147
	v_cvt_pk_bf16_f32 v147, v174, v175
	global_store_dwordx4 v[166:167], v[144:147], off
	s_cbranch_vccnz .LBB0_727
	v_mov_b64_e32 v[148:149], v[188:189]
	v_mov_b64_e32 v[150:151], v[190:191]
	v_mov_b64_e32 v[144:145], v[184:185]
	v_mov_b64_e32 v[146:147], v[186:187]
	s_cbranch_execnz .LBB0_678

; __device__ __forceinline__ unsigned cvt_pk_bf16(float lo, float hi) { unsigned r; asm volatile("v_cvt_pk_bf16_f32 %0, %1, %2" : "=v"(r) : "v"(lo), "v"(hi)); return r; }
; __device__ __forceinline__ float lo_f(unsigned w) { return __uint_as_float(w << 16); }
; __device__ __forceinline__ float hi_f(unsigned w) { return __uint_as_float(w & 0xffff0000u); }
;     __device__ __forceinline__ void operator()(f32x4 (&acc)[2][2][4][2], const Unit& u, int wr, int wc, int fr, int fq) const {
;     ...
; #pragma unroll
;         for (int ai = 0; ai < 2; ++ai)
; #pragma unroll
;             for (int m = 0; m < 4; ++m) { const size_t ro = (size_t)(row0 + ai * HALF + m * 16) * DM + col0;
; #pragma unroll
;                 for (int bj = 0; bj < 2; ++bj) { f32x4 x0, x1;
;                     if (Xf32 != nullptr) { x0 = *(const f32x4*)(Xf32 + ro + bj * HALF); x1 = *(const f32x4*)(Xf32 + ro + bj * HALF + 4); }
;                     else { const u32x4 xb = *(const u32x4*)(X + ro + bj * HALF);
;                         x0 = (f32x4){lo_f(xb.x), hi_f(xb.x), lo_f(xb.y), hi_f(xb.y)}; x1 = (f32x4){lo_f(xb.z), hi_f(xb.z), lo_f(xb.w), hi_f(xb.w)}; }
;                     x0 += gv[bj][0] * acc[ai][bj][m][0]; x1 += gv[bj][1] * acc[ai][bj][m][1];
;                     u32x4 w; w.x = cvt_pk_bf16(x0[0], x0[1]); w.y = cvt_pk_bf16(x0[2], x0[3]); w.z = cvt_pk_bf16(x1[0], x1[1]); w.w = cvt_pk_bf16(x1[2], x1[3]);
;                     *(u32x4*)(X + ro + bj * HALF) = w; } }
.LBB0_678:
	s_nop 0
	v_pk_fma_f32 v[148:149], v[112:113], v[132:133], v[148:149]
	v_pk_fma_f32 v[168:169], v[106:107], v[130:131], v[146:147]
	v_pk_fma_f32 v[146:147], v[104:105], v[128:129], v[144:145]
	v_cvt_pk_bf16_f32 v144, v148, v149
	v_pk_fma_f32 v[150:151], v[114:115], v[134:135], v[150:151]
	s_and_b64 vcc, exec, s[8:9]
	v_cvt_pk_bf16_f32 v145, v150, v151
	v_cvt_pk_bf16_f32 v146, v146, v147
	v_cvt_pk_bf16_f32 v147, v168, v169
	global_store_dwordx4 v[166:167], v[144:147], off offset:256
	s_nop 1
	v_or_b32_e32 v144, 16, v164
	v_ashrrev_i32_e32 v145, 31, v144
	v_lshlrev_b64 v[144:145], 11, v[144:145]
	v_lshl_add_u64 v[166:167], v[144:145], 0, v[162:163]
	v_lshl_add_u64 v[168:169], v[166:167], 2, s[14:15]
	s_cbranch_vccnz .LBB0_728
	v_mov_b64_e32 v[148:149], v[196:197]
	v_mov_b64_e32 v[150:151], v[198:199]
	v_mov_b64_e32 v[144:145], v[192:193]
	v_mov_b64_e32 v[146:147], v[194:195]
	v_lshl_add_u64 v[166:167], v[166:167], 1, s[20:21]
	s_cbranch_execnz .LBB0_681

; __device__ __forceinline__ unsigned cvt_pk_bf16(float lo, float hi) { unsigned r; asm volatile("v_cvt_pk_bf16_f32 %0, %1, %2" : "=v"(r) : "v"(lo), "v"(hi)); return r; }
; __device__ __forceinline__ float lo_f(unsigned w) { return __uint_as_float(w << 16); }
; __device__ __forceinline__ float hi_f(unsigned w) { return __uint_as_float(w & 0xffff0000u); }
;     __device__ __forceinline__ void operator()(f32x4 (&acc)[2][2][4][2], const Unit& u, int wr, int wc, int fr, int fq) const {
;     ...
; #pragma unroll
;         for (int ai = 0; ai < 2; ++ai)
; #pragma unroll
;             for (int m = 0; m < 4; ++m) { const size_t ro = (size_t)(row0 + ai * HALF + m * 16) * DM + col0;
; #pragma unroll
;                 for (int bj = 0; bj < 2; ++bj) { f32x4 x0, x1;
;                     if (Xf32 != nullptr) { x0 = *(const f32x4*)(Xf32 + ro + bj * HALF); x1 = *(const f32x4*)(Xf32 + ro + bj * HALF + 4); }
;                     else { const u32x4 xb = *(const u32x4*)(X + ro + bj * HALF);
;                         x0 = (f32x4){lo_f(xb.x), hi_f(xb.x), lo_f(xb.y), hi_f(xb.y)}; x1 = (f32x4){lo_f(xb.z), hi_f(xb.z), lo_f(xb.w), hi_f(xb.w)}; }
;                     x0 += gv[bj][0] * acc[ai][bj][m][0]; x1 += gv[bj][1] * acc[ai][bj][m][1];
;                     u32x4 w; w.x = cvt_pk_bf16(x0[0], x0[1]); w.y = cvt_pk_bf16(x0[2], x0[3]); w.z = cvt_pk_bf16(x1[0], x1[1]); w.w = cvt_pk_bf16(x1[2], x1[3]);
;                     *(u32x4*)(X + ro + bj * HALF) = w; } }
.LBB0_681:
	s_nop 0
	v_pk_fma_f32 v[174:175], v[110:111], v[138:139], v[146:147]
	v_pk_fma_f32 v[146:147], v[108:109], v[136:137], v[144:145]
	s_and_b64 vcc, exec, s[8:9]
	s_nop 0
	v_pk_fma_f32 v[150:151], v[118:119], v[142:143], v[150:151]
	v_pk_fma_f32 v[148:149], v[116:117], v[140:141], v[148:149]
	s_nop 0
	v_cvt_pk_bf16_f32 v144, v148, v149
	v_cvt_pk_bf16_f32 v145, v150, v151
	v_cvt_pk_bf16_f32 v146, v146, v147
	v_cvt_pk_bf16_f32 v147, v174, v175
	global_store_dwordx4 v[166:167], v[144:147], off
	s_cbranch_vccnz .LBB0_729
	v_mov_b64_e32 v[148:149], v[204:205]
	v_mov_b64_e32 v[150:151], v[206:207]
	v_mov_b64_e32 v[144:145], v[200:201]
	v_mov_b64_e32 v[146:147], v[202:203]
	s_cbranch_execnz .LBB0_684

; __device__ __forceinline__ unsigned cvt_pk_bf16(float lo, float hi) { unsigned r; asm volatile("v_cvt_pk_bf16_f32 %0, %1, %2" : "=v"(r) : "v"(lo), "v"(hi)); return r; }
; __device__ __forceinline__ float lo_f(unsigned w) { return __uint_as_float(w << 16); }
; __device__ __forceinline__ float hi_f(unsigned w) { return __uint_as_float(w & 0xffff0000u); }
;     __device__ __forceinline__ void operator()(f32x4 (&acc)[2][2][4][2], const Unit& u, int wr, int wc, int fr, int fq) const {
;     ...
; #pragma unroll
;         for (int ai = 0; ai < 2; ++ai)
; #pragma unroll
;             for (int m = 0; m < 4; ++m) { const size_t ro = (size_t)(row0 + ai * HALF + m * 16) * DM + col0;
; #pragma unroll
;                 for (int bj = 0; bj < 2; ++bj) { f32x4 x0, x1;
;                     if (Xf32 != nullptr) { x0 = *(const f32x4*)(Xf32 + ro + bj * HALF); x1 = *(const f32x4*)(Xf32 + ro + bj * HALF + 4); }
;                     else { const u32x4 xb = *(const u32x4*)(X + ro + bj * HALF);
;                         x0 = (f32x4){lo_f(xb.x), hi_f(xb.x), lo_f(xb.y), hi_f(xb.y)}; x1 = (f32x4){lo_f(xb.z), hi_f(xb.z), lo_f(xb.w), hi_f(xb.w)}; }
;                     x0 += gv[bj][0] * acc[ai][bj][m][0]; x1 += gv[bj][1] * acc[ai][bj][m][1];
;                     u32x4 w; w.x = cvt_pk_bf16(x0[0], x0[1]); w.y = cvt_pk_bf16(x0[2], x0[3]); w.z = cvt_pk_bf16(x1[0], x1[1]); w.w = cvt_pk_bf16(x1[2], x1[3]);
;                     *(u32x4*)(X + ro + bj * HALF) = w; } }
.LBB0_684:
	s_nop 0
	v_pk_fma_f32 v[148:149], v[96:97], v[132:133], v[148:149]
	v_pk_fma_f32 v[168:169], v[90:91], v[130:131], v[146:147]
	v_pk_fma_f32 v[146:147], v[88:89], v[128:129], v[144:145]
	v_cvt_pk_bf16_f32 v144, v148, v149
	v_pk_fma_f32 v[150:151], v[98:99], v[134:135], v[150:151]
	s_and_b64 vcc, exec, s[8:9]
	v_cvt_pk_bf16_f32 v145, v150, v151
	v_cvt_pk_bf16_f32 v146, v146, v147
	v_cvt_pk_bf16_f32 v147, v168, v169
	global_store_dwordx4 v[166:167], v[144:147], off offset:256
	s_nop 1
	v_or_b32_e32 v144, 32, v164
	v_ashrrev_i32_e32 v145, 31, v144
	v_lshlrev_b64 v[144:145], 11, v[144:145]
	v_lshl_add_u64 v[166:167], v[144:145], 0, v[162:163]
	v_lshl_add_u64 v[168:169], v[166:167], 2, s[14:15]
	s_cbranch_vccnz .LBB0_730
	v_mov_b64_e32 v[148:149], v[212:213]
	v_mov_b64_e32 v[150:151], v[214:215]
	v_mov_b64_e32 v[144:145], v[208:209]
	v_mov_b64_e32 v[146:147], v[210:211]
	v_lshl_add_u64 v[166:167], v[166:167], 1, s[20:21]
	s_cbranch_execnz .LBB0_687

; __device__ __forceinline__ unsigned cvt_pk_bf16(float lo, float hi) { unsigned r; asm volatile("v_cvt_pk_bf16_f32 %0, %1, %2" : "=v"(r) : "v"(lo), "v"(hi)); return r; }
; __device__ __forceinline__ float lo_f(unsigned w) { return __uint_as_float(w << 16); }
; __device__ __forceinline__ float hi_f(unsigned w) { return __uint_as_float(w & 0xffff0000u); }
;     __device__ __forceinline__ void operator()(f32x4 (&acc)[2][2][4][2], const Unit& u, int wr, int wc, int fr, int fq) const {
;     ...
; #pragma unroll
;         for (int ai = 0; ai < 2; ++ai)
; #pragma unroll
;             for (int m = 0; m < 4; ++m) { const size_t ro = (size_t)(row0 + ai * HALF + m * 16) * DM + col0;
; #pragma unroll
;                 for (int bj = 0; bj < 2; ++bj) { f32x4 x0, x1;
;                     if (Xf32 != nullptr) { x0 = *(const f32x4*)(Xf32 + ro + bj * HALF); x1 = *(const f32x4*)(Xf32 + ro + bj * HALF + 4); }
;                     else { const u32x4 xb = *(const u32x4*)(X + ro + bj * HALF);
;                         x0 = (f32x4){lo_f(xb.x), hi_f(xb.x), lo_f(xb.y), hi_f(xb.y)}; x1 = (f32x4){lo_f(xb.z), hi_f(xb.z), lo_f(xb.w), hi_f(xb.w)}; }
;                     x0 += gv[bj][0] * acc[ai][bj][m][0]; x1 += gv[bj][1] * acc[ai][bj][m][1];
;                     u32x4 w; w.x = cvt_pk_bf16(x0[0], x0[1]); w.y = cvt_pk_bf16(x0[2], x0[3]); w.z = cvt_pk_bf16(x1[0], x1[1]); w.w = cvt_pk_bf16(x1[2], x1[3]);
;                     *(u32x4*)(X + ro + bj * HALF) = w; } }
.LBB0_687:
	s_nop 0
	v_pk_fma_f32 v[174:175], v[94:95], v[138:139], v[146:147]
	v_pk_fma_f32 v[146:147], v[92:93], v[136:137], v[144:145]
	s_and_b64 vcc, exec, s[8:9]
	s_nop 0
	v_pk_fma_f32 v[150:151], v[102:103], v[142:143], v[150:151]
	v_pk_fma_f32 v[148:149], v[100:101], v[140:141], v[148:149]
	s_nop 0
	v_cvt_pk_bf16_f32 v144, v148, v149
	v_cvt_pk_bf16_f32 v145, v150, v151
	v_cvt_pk_bf16_f32 v146, v146, v147
	v_cvt_pk_bf16_f32 v147, v174, v175
	global_store_dwordx4 v[166:167], v[144:147], off
	s_cbranch_vccnz .LBB0_731
	v_mov_b64_e32 v[148:149], v[230:231]
	v_mov_b64_e32 v[150:151], v[232:233]
	v_mov_b64_e32 v[144:145], v[226:227]
	v_mov_b64_e32 v[146:147], v[228:229]
	s_cbranch_execnz .LBB0_690

; __device__ __forceinline__ unsigned cvt_pk_bf16(float lo, float hi) { unsigned r; asm volatile("v_cvt_pk_bf16_f32 %0, %1, %2" : "=v"(r) : "v"(lo), "v"(hi)); return r; }
; __device__ __forceinline__ float lo_f(unsigned w) { return __uint_as_float(w << 16); }
; __device__ __forceinline__ float hi_f(unsigned w) { return __uint_as_float(w & 0xffff0000u); }
;     __device__ __forceinline__ void operator()(f32x4 (&acc)[2][2][4][2], const Unit& u, int wr, int wc, int fr, int fq) const {
;     ...
; #pragma unroll
;         for (int ai = 0; ai < 2; ++ai)
; #pragma unroll
;             for (int m = 0; m < 4; ++m) { const size_t ro = (size_t)(row0 + ai * HALF + m * 16) * DM + col0;
; #pragma unroll
;                 for (int bj = 0; bj < 2; ++bj) { f32x4 x0, x1;
;                     if (Xf32 != nullptr) { x0 = *(const f32x4*)(Xf32 + ro + bj * HALF); x1 = *(const f32x4*)(Xf32 + ro + bj * HALF + 4); }
;                     else { const u32x4 xb = *(const u32x4*)(X + ro + bj * HALF);
;                         x0 = (f32x4){lo_f(xb.x), hi_f(xb.x), lo_f(xb.y), hi_f(xb.y)}; x1 = (f32x4){lo_f(xb.z), hi_f(xb.z), lo_f(xb.w), hi_f(xb.w)}; }
;                     x0 += gv[bj][0] * acc[ai][bj][m][0]; x1 += gv[bj][1] * acc[ai][bj][m][1];
;                     u32x4 w; w.x = cvt_pk_bf16(x0[0], x0[1]); w.y = cvt_pk_bf16(x0[2], x0[3]); w.z = cvt_pk_bf16(x1[0], x1[1]); w.w = cvt_pk_bf16(x1[2], x1[3]);
;                     *(u32x4*)(X + ro + bj * HALF) = w; } }
.LBB0_690:
	s_nop 0
	v_pk_fma_f32 v[148:149], v[80:81], v[132:133], v[148:149]
	v_pk_fma_f32 v[168:169], v[74:75], v[130:131], v[146:147]
	v_pk_fma_f32 v[146:147], v[72:73], v[128:129], v[144:145]
	v_cvt_pk_bf16_f32 v144, v148, v149
	v_pk_fma_f32 v[150:151], v[82:83], v[134:135], v[150:151]
	s_and_b64 vcc, exec, s[8:9]
	v_cvt_pk_bf16_f32 v145, v150, v151
	v_cvt_pk_bf16_f32 v146, v146, v147
	v_cvt_pk_bf16_f32 v147, v168, v169
	global_store_dwordx4 v[166:167], v[144:147], off offset:256
	s_nop 1
	v_or_b32_e32 v144, 48, v164
	v_ashrrev_i32_e32 v145, 31, v144
	v_lshlrev_b64 v[144:145], 11, v[144:145]
	v_lshl_add_u64 v[166:167], v[144:145], 0, v[162:163]
	v_lshl_add_u64 v[168:169], v[166:167], 2, s[14:15]
	s_cbranch_vccnz .LBB0_732
	v_mov_b64_e32 v[148:149], v[238:239]
	v_mov_b64_e32 v[150:151], v[240:241]
	v_mov_b64_e32 v[144:145], v[234:235]
	v_mov_b64_e32 v[146:147], v[236:237]
	v_lshl_add_u64 v[166:167], v[166:167], 1, s[20:21]
	s_cbranch_execnz .LBB0_693

; __device__ __forceinline__ unsigned cvt_pk_bf16(float lo, float hi) { unsigned r; asm volatile("v_cvt_pk_bf16_f32 %0, %1, %2" : "=v"(r) : "v"(lo), "v"(hi)); return r; }
; __device__ __forceinline__ float lo_f(unsigned w) { return __uint_as_float(w << 16); }
; __device__ __forceinline__ float hi_f(unsigned w) { return __uint_as_float(w & 0xffff0000u); }
;     __device__ __forceinline__ void operator()(f32x4 (&acc)[2][2][4][2], const Unit& u, int wr, int wc, int fr, int fq) const {
;     ...
; #pragma unroll
;         for (int ai = 0; ai < 2; ++ai)
; #pragma unroll
;             for (int m = 0; m < 4; ++m) { const size_t ro = (size_t)(row0 + ai * HALF + m * 16) * DM + col0;
; #pragma unroll
;                 for (int bj = 0; bj < 2; ++bj) { f32x4 x0, x1;
;                     if (Xf32 != nullptr) { x0 = *(const f32x4*)(Xf32 + ro + bj * HALF); x1 = *(const f32x4*)(Xf32 + ro + bj * HALF + 4); }
;                     else { const u32x4 xb = *(const u32x4*)(X + ro + bj * HALF);
;                         x0 = (f32x4){lo_f(xb.x), hi_f(xb.x), lo_f(xb.y), hi_f(xb.y)}; x1 = (f32x4){lo_f(xb.z), hi_f(xb.z), lo_f(xb.w), hi_f(xb.w)}; }
;                     x0 += gv[bj][0] * acc[ai][bj][m][0]; x1 += gv[bj][1] * acc[ai][bj][m][1];
;                     u32x4 w; w.x = cvt_pk_bf16(x0[0], x0[1]); w.y = cvt_pk_bf16(x0[2], x0[3]); w.z = cvt_pk_bf16(x1[0], x1[1]); w.w = cvt_pk_bf16(x1[2], x1[3]);
;                     *(u32x4*)(X + ro + bj * HALF) = w; } }
.LBB0_693:
	s_nop 0
	v_pk_fma_f32 v[174:175], v[78:79], v[138:139], v[146:147]
	v_pk_fma_f32 v[146:147], v[76:77], v[136:137], v[144:145]
	s_and_b64 vcc, exec, s[8:9]
	s_nop 0
	v_pk_fma_f32 v[150:151], v[86:87], v[142:143], v[150:151]
	v_pk_fma_f32 v[148:149], v[84:85], v[140:141], v[148:149]
	s_nop 0
	v_cvt_pk_bf16_f32 v144, v148, v149
	v_cvt_pk_bf16_f32 v145, v150, v151
	v_cvt_pk_bf16_f32 v146, v146, v147
	v_cvt_pk_bf16_f32 v147, v174, v175
	global_store_dwordx4 v[166:167], v[144:147], off
	s_cbranch_vccnz .LBB0_733
	v_mov_b32_e32 v242, 0x60000
	v_lshl_add_u64 v[180:181], v[244:245], 0, v[242:243]
	global_load_dwordx4 v[176:179], v[180:181], off offset:528
	global_load_dwordx4 v[180:183], v[180:181], off offset:512
	v_mov_b32_e32 v242, 0x100000
	v_lshl_add_u64 v[188:189], v[244:245], 0, v[242:243]
	global_load_dwordx4 v[184:187], v[188:189], off offset:16
	global_load_dwordx4 v[188:191], v[188:189], off
	v_mov_b32_e32 v242, 0x100000
	v_lshl_add_u64 v[196:197], v[244:245], 0, v[242:243]
	global_load_dwordx4 v[192:195], v[196:197], off offset:528
	global_load_dwordx4 v[196:199], v[196:197], off offset:512
	v_mov_b32_e32 v242, 0x120000
	v_lshl_add_u64 v[204:205], v[244:245], 0, v[242:243]
	global_load_dwordx4 v[200:203], v[204:205], off offset:16
	global_load_dwordx4 v[204:207], v[204:205], off
	v_mov_b32_e32 v242, 0x120000
	v_lshl_add_u64 v[212:213], v[244:245], 0, v[242:243]
	global_load_dwordx4 v[208:211], v[212:213], off offset:528
	global_load_dwordx4 v[212:215], v[212:213], off offset:512
	v_mov_b32_e32 v242, 0x140000
	v_lshl_add_u64 v[230:231], v[244:245], 0, v[242:243]
	global_load_dwordx4 v[226:229], v[230:231], off offset:16
	global_load_dwordx4 v[230:233], v[230:231], off
	v_mov_b32_e32 v242, 0x140000
	v_lshl_add_u64 v[238:239], v[244:245], 0, v[242:243]
	global_load_dwordx4 v[234:237], v[238:239], off offset:528
	global_load_dwordx4 v[238:241], v[238:239], off offset:512
	s_cbranch_execnz .LBB0_696

; __device__ __forceinline__ unsigned cvt_pk_bf16(float lo, float hi) { unsigned r; asm volatile("v_cvt_pk_bf16_f32 %0, %1, %2" : "=v"(r) : "v"(lo), "v"(hi)); return r; }
; __device__ __forceinline__ float lo_f(unsigned w) { return __uint_as_float(w << 16); }
; __device__ __forceinline__ float hi_f(unsigned w) { return __uint_as_float(w & 0xffff0000u); }
;     __device__ __forceinline__ void operator()(f32x4 (&acc)[2][2][4][2], const Unit& u, int wr, int wc, int fr, int fq) const {
;     ...
; #pragma unroll
;         for (int ai = 0; ai < 2; ++ai)
; #pragma unroll
;             for (int m = 0; m < 4; ++m) { const size_t ro = (size_t)(row0 + ai * HALF + m * 16) * DM + col0;
; #pragma unroll
;                 for (int bj = 0; bj < 2; ++bj) { f32x4 x0, x1;
;                     if (Xf32 != nullptr) { x0 = *(const f32x4*)(Xf32 + ro + bj * HALF); x1 = *(const f32x4*)(Xf32 + ro + bj * HALF + 4); }
;                     else { const u32x4 xb = *(const u32x4*)(X + ro + bj * HALF);
;                         x0 = (f32x4){lo_f(xb.x), hi_f(xb.x), lo_f(xb.y), hi_f(xb.y)}; x1 = (f32x4){lo_f(xb.z), hi_f(xb.z), lo_f(xb.w), hi_f(xb.w)}; }
;                     x0 += gv[bj][0] * acc[ai][bj][m][0]; x1 += gv[bj][1] * acc[ai][bj][m][1];
;                     u32x4 w; w.x = cvt_pk_bf16(x0[0], x0[1]); w.y = cvt_pk_bf16(x0[2], x0[3]); w.z = cvt_pk_bf16(x1[0], x1[1]); w.w = cvt_pk_bf16(x1[2], x1[3]);
;                     *(u32x4*)(X + ro + bj * HALF) = w; } }
.LBB0_696:
	s_waitcnt vmcnt(0)
	v_mov_b64_e32 v[148:149], v[180:181]
	v_mov_b64_e32 v[150:151], v[182:183]
	v_mov_b64_e32 v[144:145], v[176:177]
	v_mov_b64_e32 v[146:147], v[178:179]
	v_pk_fma_f32 v[150:151], v[70:71], v[134:135], v[150:151]
	v_pk_fma_f32 v[148:149], v[68:69], v[132:133], v[148:149]
	v_pk_fma_f32 v[168:169], v[66:67], v[130:131], v[146:147]
	v_pk_fma_f32 v[146:147], v[64:65], v[128:129], v[144:145]
	v_cvt_pk_bf16_f32 v144, v148, v149
	v_cvt_pk_bf16_f32 v145, v150, v151
	s_mov_b64 s[50:51], 0x40000
	v_cvt_pk_bf16_f32 v146, v146, v147
	v_cvt_pk_bf16_f32 v147, v168, v169
	global_store_dwordx4 v[166:167], v[144:147], off offset:256
	s_and_b64 vcc, exec, s[8:9]
	s_nop 0
	v_lshlrev_b64 v[144:145], 11, v[164:165]
	v_lshl_add_u64 v[144:145], v[144:145], 0, v[162:163]
	v_lshl_add_u64 v[166:167], v[144:145], 0, s[50:51]
	v_lshl_add_u64 v[168:169], v[166:167], 2, s[14:15]
	s_cbranch_vccnz .LBB0_734
	v_mov_b64_e32 v[148:149], v[188:189]
	v_mov_b64_e32 v[150:151], v[190:191]
	v_mov_b64_e32 v[144:145], v[184:185]
	v_mov_b64_e32 v[146:147], v[186:187]
	v_lshl_add_u64 v[166:167], v[166:167], 1, s[20:21]
	s_cbranch_execnz .LBB0_699

; __device__ __forceinline__ unsigned cvt_pk_bf16(float lo, float hi) { unsigned r; asm volatile("v_cvt_pk_bf16_f32 %0, %1, %2" : "=v"(r) : "v"(lo), "v"(hi)); return r; }
; __device__ __forceinline__ float lo_f(unsigned w) { return __uint_as_float(w << 16); }
; __device__ __forceinline__ float hi_f(unsigned w) { return __uint_as_float(w & 0xffff0000u); }
;     __device__ __forceinline__ void operator()(f32x4 (&acc)[2][2][4][2], const Unit& u, int wr, int wc, int fr, int fq) const {
;     ...
; #pragma unroll
;         for (int ai = 0; ai < 2; ++ai)
; #pragma unroll
;             for (int m = 0; m < 4; ++m) { const size_t ro = (size_t)(row0 + ai * HALF + m * 16) * DM + col0;
; #pragma unroll
;                 for (int bj = 0; bj < 2; ++bj) { f32x4 x0, x1;
;                     if (Xf32 != nullptr) { x0 = *(const f32x4*)(Xf32 + ro + bj * HALF); x1 = *(const f32x4*)(Xf32 + ro + bj * HALF + 4); }
;                     else { const u32x4 xb = *(const u32x4*)(X + ro + bj * HALF);
;                         x0 = (f32x4){lo_f(xb.x), hi_f(xb.x), lo_f(xb.y), hi_f(xb.y)}; x1 = (f32x4){lo_f(xb.z), hi_f(xb.z), lo_f(xb.w), hi_f(xb.w)}; }
;                     x0 += gv[bj][0] * acc[ai][bj][m][0]; x1 += gv[bj][1] * acc[ai][bj][m][1];
;                     u32x4 w; w.x = cvt_pk_bf16(x0[0], x0[1]); w.y = cvt_pk_bf16(x0[2], x0[3]); w.z = cvt_pk_bf16(x1[0], x1[1]); w.w = cvt_pk_bf16(x1[2], x1[3]);
;                     *(u32x4*)(X + ro + bj * HALF) = w; } }
.LBB0_699:
	s_nop 0
	v_pk_fma_f32 v[174:175], v[58:59], v[138:139], v[146:147]
	v_pk_fma_f32 v[146:147], v[56:57], v[136:137], v[144:145]
	s_and_b64 vcc, exec, s[8:9]
	s_nop 0
	v_pk_fma_f32 v[150:151], v[62:63], v[142:143], v[150:151]
	v_pk_fma_f32 v[148:149], v[60:61], v[140:141], v[148:149]
	s_nop 0
	v_cvt_pk_bf16_f32 v144, v148, v149
	v_cvt_pk_bf16_f32 v145, v150, v151
	v_cvt_pk_bf16_f32 v146, v146, v147
	v_cvt_pk_bf16_f32 v147, v174, v175
	global_store_dwordx4 v[166:167], v[144:147], off
	s_cbranch_vccnz .LBB0_735
	v_mov_b64_e32 v[148:149], v[196:197]
	v_mov_b64_e32 v[150:151], v[198:199]
	v_mov_b64_e32 v[144:145], v[192:193]
	v_mov_b64_e32 v[146:147], v[194:195]
	s_cbranch_execnz .LBB0_702

; __device__ __forceinline__ unsigned cvt_pk_bf16(float lo, float hi) { unsigned r; asm volatile("v_cvt_pk_bf16_f32 %0, %1, %2" : "=v"(r) : "v"(lo), "v"(hi)); return r; }
; __device__ __forceinline__ float lo_f(unsigned w) { return __uint_as_float(w << 16); }
; __device__ __forceinline__ float hi_f(unsigned w) { return __uint_as_float(w & 0xffff0000u); }
;     __device__ __forceinline__ void operator()(f32x4 (&acc)[2][2][4][2], const Unit& u, int wr, int wc, int fr, int fq) const {
;     ...
; #pragma unroll
;         for (int ai = 0; ai < 2; ++ai)
; #pragma unroll
;             for (int m = 0; m < 4; ++m) { const size_t ro = (size_t)(row0 + ai * HALF + m * 16) * DM + col0;
; #pragma unroll
;                 for (int bj = 0; bj < 2; ++bj) { f32x4 x0, x1;
;                     if (Xf32 != nullptr) { x0 = *(const f32x4*)(Xf32 + ro + bj * HALF); x1 = *(const f32x4*)(Xf32 + ro + bj * HALF + 4); }
;                     else { const u32x4 xb = *(const u32x4*)(X + ro + bj * HALF);
;                         x0 = (f32x4){lo_f(xb.x), hi_f(xb.x), lo_f(xb.y), hi_f(xb.y)}; x1 = (f32x4){lo_f(xb.z), hi_f(xb.z), lo_f(xb.w), hi_f(xb.w)}; }
;                     x0 += gv[bj][0] * acc[ai][bj][m][0]; x1 += gv[bj][1] * acc[ai][bj][m][1];
;                     u32x4 w; w.x = cvt_pk_bf16(x0[0], x0[1]); w.y = cvt_pk_bf16(x0[2], x0[3]); w.z = cvt_pk_bf16(x1[0], x1[1]); w.w = cvt_pk_bf16(x1[2], x1[3]);
;                     *(u32x4*)(X + ro + bj * HALF) = w; } }
.LBB0_702:
	s_nop 0
	v_pk_fma_f32 v[150:151], v[50:51], v[134:135], v[150:151]
	v_pk_fma_f32 v[148:149], v[48:49], v[132:133], v[148:149]
	v_pk_fma_f32 v[168:169], v[42:43], v[130:131], v[146:147]
	v_pk_fma_f32 v[146:147], v[40:41], v[128:129], v[144:145]
	v_cvt_pk_bf16_f32 v144, v148, v149
	v_cvt_pk_bf16_f32 v145, v150, v151
	s_mov_b64 s[50:51], 0x48000
	v_cvt_pk_bf16_f32 v146, v146, v147
	v_cvt_pk_bf16_f32 v147, v168, v169
	global_store_dwordx4 v[166:167], v[144:147], off offset:256
	s_and_b64 vcc, exec, s[8:9]
	s_nop 0
	v_lshlrev_b64 v[144:145], 11, v[164:165]
	v_lshl_add_u64 v[144:145], v[144:145], 0, v[162:163]
	v_lshl_add_u64 v[166:167], v[144:145], 0, s[50:51]
	v_lshl_add_u64 v[168:169], v[166:167], 2, s[14:15]
	s_cbranch_vccnz .LBB0_736
	v_mov_b64_e32 v[148:149], v[204:205]
	v_mov_b64_e32 v[150:151], v[206:207]
	v_mov_b64_e32 v[144:145], v[200:201]
	v_mov_b64_e32 v[146:147], v[202:203]
	v_lshl_add_u64 v[166:167], v[166:167], 1, s[20:21]
	s_cbranch_execnz .LBB0_705

; __device__ __forceinline__ unsigned cvt_pk_bf16(float lo, float hi) { unsigned r; asm volatile("v_cvt_pk_bf16_f32 %0, %1, %2" : "=v"(r) : "v"(lo), "v"(hi)); return r; }
; __device__ __forceinline__ float lo_f(unsigned w) { return __uint_as_float(w << 16); }
; __device__ __forceinline__ float hi_f(unsigned w) { return __uint_as_float(w & 0xffff0000u); }
;     __device__ __forceinline__ void operator()(f32x4 (&acc)[2][2][4][2], const Unit& u, int wr, int wc, int fr, int fq) const {
;     ...
; #pragma unroll
;         for (int ai = 0; ai < 2; ++ai)
; #pragma unroll
;             for (int m = 0; m < 4; ++m) { const size_t ro = (size_t)(row0 + ai * HALF + m * 16) * DM + col0;
; #pragma unroll
;                 for (int bj = 0; bj < 2; ++bj) { f32x4 x0, x1;
;                     if (Xf32 != nullptr) { x0 = *(const f32x4*)(Xf32 + ro + bj * HALF); x1 = *(const f32x4*)(Xf32 + ro + bj * HALF + 4); }
;                     else { const u32x4 xb = *(const u32x4*)(X + ro + bj * HALF);
;                         x0 = (f32x4){lo_f(xb.x), hi_f(xb.x), lo_f(xb.y), hi_f(xb.y)}; x1 = (f32x4){lo_f(xb.z), hi_f(xb.z), lo_f(xb.w), hi_f(xb.w)}; }
;                     x0 += gv[bj][0] * acc[ai][bj][m][0]; x1 += gv[bj][1] * acc[ai][bj][m][1];
;                     u32x4 w; w.x = cvt_pk_bf16(x0[0], x0[1]); w.y = cvt_pk_bf16(x0[2], x0[3]); w.z = cvt_pk_bf16(x1[0], x1[1]); w.w = cvt_pk_bf16(x1[2], x1[3]);
;                     *(u32x4*)(X + ro + bj * HALF) = w; } }
.LBB0_705:
	s_nop 0
	v_pk_fma_f32 v[174:175], v[46:47], v[138:139], v[146:147]
	v_pk_fma_f32 v[146:147], v[44:45], v[136:137], v[144:145]
	s_and_b64 vcc, exec, s[8:9]
	s_nop 0
	v_pk_fma_f32 v[150:151], v[54:55], v[142:143], v[150:151]
	v_pk_fma_f32 v[148:149], v[52:53], v[140:141], v[148:149]
	s_nop 0
	v_cvt_pk_bf16_f32 v144, v148, v149
	v_cvt_pk_bf16_f32 v145, v150, v151
	v_cvt_pk_bf16_f32 v146, v146, v147
	v_cvt_pk_bf16_f32 v147, v174, v175
	global_store_dwordx4 v[166:167], v[144:147], off
	s_cbranch_vccnz .LBB0_737
	v_mov_b64_e32 v[148:149], v[212:213]
	v_mov_b64_e32 v[150:151], v[214:215]
	v_mov_b64_e32 v[144:145], v[208:209]
	v_mov_b64_e32 v[146:147], v[210:211]
	s_cbranch_execnz .LBB0_708

; __device__ __forceinline__ unsigned cvt_pk_bf16(float lo, float hi) { unsigned r; asm volatile("v_cvt_pk_bf16_f32 %0, %1, %2" : "=v"(r) : "v"(lo), "v"(hi)); return r; }
; __device__ __forceinline__ float lo_f(unsigned w) { return __uint_as_float(w << 16); }
; __device__ __forceinline__ float hi_f(unsigned w) { return __uint_as_float(w & 0xffff0000u); }
;     __device__ __forceinline__ void operator()(f32x4 (&acc)[2][2][4][2], const Unit& u, int wr, int wc, int fr, int fq) const {
;     ...
; #pragma unroll
;         for (int ai = 0; ai < 2; ++ai)
; #pragma unroll
;             for (int m = 0; m < 4; ++m) { const size_t ro = (size_t)(row0 + ai * HALF + m * 16) * DM + col0;
; #pragma unroll
;                 for (int bj = 0; bj < 2; ++bj) { f32x4 x0, x1;
;                     if (Xf32 != nullptr) { x0 = *(const f32x4*)(Xf32 + ro + bj * HALF); x1 = *(const f32x4*)(Xf32 + ro + bj * HALF + 4); }
;                     else { const u32x4 xb = *(const u32x4*)(X + ro + bj * HALF);
;                         x0 = (f32x4){lo_f(xb.x), hi_f(xb.x), lo_f(xb.y), hi_f(xb.y)}; x1 = (f32x4){lo_f(xb.z), hi_f(xb.z), lo_f(xb.w), hi_f(xb.w)}; }
;                     x0 += gv[bj][0] * acc[ai][bj][m][0]; x1 += gv[bj][1] * acc[ai][bj][m][1];
;                     u32x4 w; w.x = cvt_pk_bf16(x0[0], x0[1]); w.y = cvt_pk_bf16(x0[2], x0[3]); w.z = cvt_pk_bf16(x1[0], x1[1]); w.w = cvt_pk_bf16(x1[2], x1[3]);
;                     *(u32x4*)(X + ro + bj * HALF) = w; } }
.LBB0_708:
	s_nop 0
	v_pk_fma_f32 v[150:151], v[34:35], v[134:135], v[150:151]
	v_pk_fma_f32 v[148:149], v[32:33], v[132:133], v[148:149]
	v_pk_fma_f32 v[168:169], v[26:27], v[130:131], v[146:147]
	v_pk_fma_f32 v[146:147], v[24:25], v[128:129], v[144:145]
	v_cvt_pk_bf16_f32 v144, v148, v149
	v_cvt_pk_bf16_f32 v145, v150, v151
	s_mov_b64 s[50:51], 0x50000
	v_cvt_pk_bf16_f32 v146, v146, v147
	v_cvt_pk_bf16_f32 v147, v168, v169
	global_store_dwordx4 v[166:167], v[144:147], off offset:256
	s_and_b64 vcc, exec, s[8:9]
	s_nop 0
	v_lshlrev_b64 v[144:145], 11, v[164:165]
	v_lshl_add_u64 v[144:145], v[144:145], 0, v[162:163]
	v_lshl_add_u64 v[166:167], v[144:145], 0, s[50:51]
	v_lshl_add_u64 v[168:169], v[166:167], 2, s[14:15]
	s_cbranch_vccnz .LBB0_738
	v_mov_b64_e32 v[148:149], v[230:231]
	v_mov_b64_e32 v[150:151], v[232:233]
	v_mov_b64_e32 v[144:145], v[226:227]
	v_mov_b64_e32 v[146:147], v[228:229]
	v_lshl_add_u64 v[166:167], v[166:167], 1, s[20:21]
	s_cbranch_execnz .LBB0_711

; __device__ __forceinline__ unsigned cvt_pk_bf16(float lo, float hi) { unsigned r; asm volatile("v_cvt_pk_bf16_f32 %0, %1, %2" : "=v"(r) : "v"(lo), "v"(hi)); return r; }
; __device__ __forceinline__ float lo_f(unsigned w) { return __uint_as_float(w << 16); }
; __device__ __forceinline__ float hi_f(unsigned w) { return __uint_as_float(w & 0xffff0000u); }
;     __device__ __forceinline__ void operator()(f32x4 (&acc)[2][2][4][2], const Unit& u, int wr, int wc, int fr, int fq) const {
;     ...
; #pragma unroll
;         for (int ai = 0; ai < 2; ++ai)
; #pragma unroll
;             for (int m = 0; m < 4; ++m) { const size_t ro = (size_t)(row0 + ai * HALF + m * 16) * DM + col0;
; #pragma unroll
;                 for (int bj = 0; bj < 2; ++bj) { f32x4 x0, x1;
;                     if (Xf32 != nullptr) { x0 = *(const f32x4*)(Xf32 + ro + bj * HALF); x1 = *(const f32x4*)(Xf32 + ro + bj * HALF + 4); }
;                     else { const u32x4 xb = *(const u32x4*)(X + ro + bj * HALF);
;                         x0 = (f32x4){lo_f(xb.x), hi_f(xb.x), lo_f(xb.y), hi_f(xb.y)}; x1 = (f32x4){lo_f(xb.z), hi_f(xb.z), lo_f(xb.w), hi_f(xb.w)}; }
;                     x0 += gv[bj][0] * acc[ai][bj][m][0]; x1 += gv[bj][1] * acc[ai][bj][m][1];
;                     u32x4 w; w.x = cvt_pk_bf16(x0[0], x0[1]); w.y = cvt_pk_bf16(x0[2], x0[3]); w.z = cvt_pk_bf16(x1[0], x1[1]); w.w = cvt_pk_bf16(x1[2], x1[3]);
;                     *(u32x4*)(X + ro + bj * HALF) = w; } }
.LBB0_711:
	s_nop 0
	v_pk_fma_f32 v[174:175], v[30:31], v[138:139], v[146:147]
	v_pk_fma_f32 v[146:147], v[28:29], v[136:137], v[144:145]
	s_and_b64 vcc, exec, s[8:9]
	s_nop 0
	v_pk_fma_f32 v[150:151], v[38:39], v[142:143], v[150:151]
	v_pk_fma_f32 v[148:149], v[36:37], v[140:141], v[148:149]
	s_nop 0
	v_cvt_pk_bf16_f32 v144, v148, v149
	v_cvt_pk_bf16_f32 v145, v150, v151
	v_cvt_pk_bf16_f32 v146, v146, v147
	v_cvt_pk_bf16_f32 v147, v174, v175
	global_store_dwordx4 v[166:167], v[144:147], off
	s_cbranch_vccnz .LBB0_739
	v_mov_b64_e32 v[148:149], v[238:239]
	v_mov_b64_e32 v[150:151], v[240:241]
	v_mov_b64_e32 v[144:145], v[234:235]
	v_mov_b64_e32 v[146:147], v[236:237]
	s_cbranch_execnz .LBB0_714

; __device__ __forceinline__ unsigned cvt_pk_bf16(float lo, float hi) { unsigned r; asm volatile("v_cvt_pk_bf16_f32 %0, %1, %2" : "=v"(r) : "v"(lo), "v"(hi)); return r; }
; __device__ __forceinline__ float lo_f(unsigned w) { return __uint_as_float(w << 16); }
; __device__ __forceinline__ float hi_f(unsigned w) { return __uint_as_float(w & 0xffff0000u); }
;     __device__ __forceinline__ void operator()(f32x4 (&acc)[2][2][4][2], const Unit& u, int wr, int wc, int fr, int fq) const {
;     ...
; #pragma unroll
;         for (int ai = 0; ai < 2; ++ai)
; #pragma unroll
;             for (int m = 0; m < 4; ++m) { const size_t ro = (size_t)(row0 + ai * HALF + m * 16) * DM + col0;
; #pragma unroll
;                 for (int bj = 0; bj < 2; ++bj) { f32x4 x0, x1;
;                     if (Xf32 != nullptr) { x0 = *(const f32x4*)(Xf32 + ro + bj * HALF); x1 = *(const f32x4*)(Xf32 + ro + bj * HALF + 4); }
;                     else { const u32x4 xb = *(const u32x4*)(X + ro + bj * HALF);
;                         x0 = (f32x4){lo_f(xb.x), hi_f(xb.x), lo_f(xb.y), hi_f(xb.y)}; x1 = (f32x4){lo_f(xb.z), hi_f(xb.z), lo_f(xb.w), hi_f(xb.w)}; }
;                     x0 += gv[bj][0] * acc[ai][bj][m][0]; x1 += gv[bj][1] * acc[ai][bj][m][1];
;                     u32x4 w; w.x = cvt_pk_bf16(x0[0], x0[1]); w.y = cvt_pk_bf16(x0[2], x0[3]); w.z = cvt_pk_bf16(x1[0], x1[1]); w.w = cvt_pk_bf16(x1[2], x1[3]);
;                     *(u32x4*)(X + ro + bj * HALF) = w; } }
.LBB0_714:
	s_nop 0
	v_pk_fma_f32 v[150:151], v[18:19], v[134:135], v[150:151]
	v_pk_fma_f32 v[148:149], v[16:17], v[132:133], v[148:149]
	v_pk_fma_f32 v[168:169], v[10:11], v[130:131], v[146:147]
	v_pk_fma_f32 v[146:147], v[8:9], v[128:129], v[144:145]
	v_cvt_pk_bf16_f32 v144, v148, v149
	v_cvt_pk_bf16_f32 v145, v150, v151
	s_mov_b64 s[50:51], 0x58000
	v_cvt_pk_bf16_f32 v146, v146, v147
	v_cvt_pk_bf16_f32 v147, v168, v169
	global_store_dwordx4 v[166:167], v[144:147], off offset:256
	s_and_b64 vcc, exec, s[8:9]
	s_nop 0
	v_lshlrev_b64 v[144:145], 11, v[164:165]
	v_lshl_add_u64 v[144:145], v[144:145], 0, v[162:163]
	v_lshl_add_u64 v[166:167], v[144:145], 0, s[50:51]
	v_lshl_add_u64 v[168:169], v[166:167], 2, s[14:15]
	s_cbranch_vccnz .LBB0_740
	global_load_dwordx4 v[144:147], v[168:169], off offset:16
	global_load_dwordx4 v[148:151], v[168:169], off
	v_lshl_add_u64 v[166:167], v[166:167], 1, s[20:21]
	s_cbranch_execnz .LBB0_717
